# NSA selected-branch loop: causal mask only on last tile, block-union word via v_readlane, sel word prefetched before QK
# speedup vs baseline: 1.0195x; 1.0195x over previous
; #define LAS __attribute__((address_space(3)))
; #define OPQ_WS(name) GAS unsigned char* name = (GAS unsigned char*)P.ws; asm volatile("" : "+s"(name))
; #define ZERO_O() do { _Pragma("unroll") for (int db = 0; db < 4; ++db) _Pragma("unroll") for (int r = 0; r < 16; ++r) o[db][r] = 0.f; } while (0)
; template <int KRS, bool HAS_X, bool MIDSTORE, class Pre, class Body>
; __device__ __forceinline__ void flash_loop_pre(LAS unsigned char* lds, const TileSrc& src, int tb, int te, int tid, Pre&& pre, Body&& body) {
;     ...
;     { TileRegs<KRS, HAS_X> R0;
;       tile_load<KRS, HAS_X>(R0, src, tb, tid); if (tb + 1 < te) tile_load<KRS, HAS_X>(R, src, tb + 1, tid);
;       pre();
;       tile_store<KRS, HAS_X>(R0, lds, tid); }
;     __syncthreads();
; __device__ __forceinline__ void nsa_unit(int hk, int T, LAS unsigned char* lds, LAS float* wsf, const AttnPtrs& P) {
;     ...
;         OPQ_WS(wss);
;         TileSrc ssrc{WSP(const bf16_t, wss, WS_KS) + (size_t)hk * M * 128, nullptr, WSP(const bf16_t, wss, WS_VTN) + (size_t)(hk * 128) * M, M};
;         m = -1e30f; l = 0.f; ZERO_O();
;         flash_loop<KRS_NSA, false, true>(lds, ssrc, 0, T + 1, tid, [&](int j, const LAS unsigned char* buf, auto&& mid) __attribute__((always_inline)) {
;             const unsigned uw = __builtin_amdgcn_readfirstlane(uni[w * 8 + (j >> 5)]);
;             const bool act = ((uw >> (j & 31)) & 1u) != 0u;
.LBB0_1454:
	v_lshrrev_b32_e32 v0, 4, v170
	v_mul_lo_u32 v169, v0, s83
	v_and_b32_e32 v171, 0xf0, v189
	v_add3_u32 v0, 0, v169, v171
	v_mul_lo_u32 v194, v174, s84
	s_waitcnt vmcnt(3)
	ds_write_b128 v0, v[2:5]
	s_waitcnt vmcnt(2)
	ds_write_b128 v0, v[6:9] offset:8704
	v_add3_u32 v0, 0, v194, v168
	v_lshl_add_u64 v[2:3], s[6:7], 0, v[160:161]
	s_waitcnt vmcnt(1)
	ds_write_b128 v0, v[10:13] offset:17408
	s_waitcnt vmcnt(0)
	ds_write_b128 v0, v[14:17] offset:26624
	s_lshl_b32 s8, s56, 5
	v_lshl_add_u64 v[2:3], v[172:173], 1, v[2:3]
	s_mov_b64 s[6:7], 0x10c0a000
	v_mov_b32_e32 v14, v1
	v_mov_b32_e32 v15, v1
	s_add_i32 s10, s8, 0
	v_lshl_add_u32 v196, v180, 5, s60
	v_lshl_add_u64 v[180:181], v[2:3], 0, s[6:7]
	v_mov_b32_e32 v0, v1
	v_mov_b32_e32 v2, v1
	v_mov_b32_e32 v3, v1
	v_mov_b32_e32 v4, v1
	v_mov_b32_e32 v5, v1
	v_mov_b32_e32 v6, v1
	v_mov_b32_e32 v7, v1
	v_mov_b32_e32 v8, v1
	v_mov_b32_e32 v9, v1
	v_mov_b32_e32 v10, v1
	v_mov_b32_e32 v11, v1
	v_mov_b32_e32 v12, v1
	v_mov_b32_e32 v13, v1
	v_mov_b64_e32 v[94:95], v[14:15]
	v_mov_b64_e32 v[30:31], v[14:15]
	v_mov_b64_e32 v[46:47], v[14:15]
	v_mov_b64_e32 v[62:63], v[14:15]
	s_add_i32 s10, s10, 0x22100
	v_mul_u32_u24_e32 v195, 0x110, v165
	v_lshlrev_b32_e32 v197, 2, v186
	v_mul_u32_u24_e32 v198, 0x90, v165
	s_mov_b32 s11, 0
	v_mov_b32_e32 v200, 0xf149f2ca
	v_mov_b32_e32 v199, 0
	s_movk_i32 s60, 0x80
	v_mov_b64_e32 v[92:93], v[12:13]
	v_mov_b64_e32 v[90:91], v[10:11]
	v_mov_b64_e32 v[88:89], v[8:9]
	v_mov_b64_e32 v[86:87], v[6:7]
	v_mov_b64_e32 v[84:85], v[4:5]
	v_mov_b64_e32 v[82:83], v[2:3]
	v_mov_b64_e32 v[80:81], v[0:1]
	v_mov_b64_e32 v[28:29], v[12:13]
	v_mov_b64_e32 v[26:27], v[10:11]
	v_mov_b64_e32 v[24:25], v[8:9]
	v_mov_b64_e32 v[22:23], v[6:7]
	v_mov_b64_e32 v[20:21], v[4:5]
	v_mov_b64_e32 v[18:19], v[2:3]
	v_mov_b64_e32 v[16:17], v[0:1]
	v_mov_b64_e32 v[44:45], v[12:13]
	v_mov_b64_e32 v[42:43], v[10:11]
	v_mov_b64_e32 v[40:41], v[8:9]
	v_mov_b64_e32 v[38:39], v[6:7]
	v_mov_b64_e32 v[36:37], v[4:5]
	v_mov_b64_e32 v[34:35], v[2:3]
	v_mov_b64_e32 v[32:33], v[0:1]
	v_mov_b64_e32 v[60:61], v[12:13]
	v_mov_b64_e32 v[58:59], v[10:11]
	v_mov_b64_e32 v[56:57], v[8:9]
	v_mov_b64_e32 v[54:55], v[6:7]
	v_mov_b64_e32 v[52:53], v[4:5]
	v_mov_b64_e32 v[50:51], v[2:3]
	v_mov_b64_e32 v[48:49], v[0:1]
	s_waitcnt lgkmcnt(0)
	v_mbcnt_lo_u32_b32 v253, -1, 0
	v_mbcnt_hi_u32_b32 v253, -1, v253
	v_and_b32_e32 v253, 7, v253
	v_lshl_add_u32 v253, v253, 2, s10
	ds_read_b32 v253, v253
	s_waitcnt lgkmcnt(0)
	s_barrier
	s_and_b32 s7, s11, 1
	s_cmp_ge_i32 s11, s97
	s_cbranch_scc1 .LBB0_1456

; __device__ __forceinline__ int crow(int r, int hi) { return (r & 3) + 8 * (r >> 2) + 4 * hi; }
; __device__ __forceinline__ void nsa_unit(int hk, int T, LAS unsigned char* lds, LAS float* wsf, const AttnPtrs& P) {
;     ...
;             const unsigned uw = __builtin_amdgcn_readfirstlane(uni[w * 8 + (j >> 5)]);
;             const bool act = ((uw >> (j & 31)) & 1u) != 0u;
;             f32x16 p0, p1;
;             if (act) {
;                 qk_tile<8, KRS_NSA>(p0, p1, buf, qf, r32, hi);
;                 const unsigned mw = sel[(8 * w + qi) * 8 + (j >> 5)];
;                 const bool mine = (mw >> (j & 31)) & 1u;
; #pragma unroll
;                 for (int r = 0; r < 16; ++r) { const int key = 64 * j + crow(r, hi);
;                     if (!mine || key > tq) p0[r] = -INFINITY; if (!mine || key + 32 > tq) p1[r] = -INFINITY; }
.LBB0_1458:
	s_lshr_b32 s6, s11, 5
	s_lshl_b32 s8, 1, s11
	v_readlane_b32 s9, v253, s6
	s_and_b32 s9, s9, s8
	s_cmp_eq_u32 s9, 0
	s_cbranch_scc1 .LBB0_1464
	s_mul_i32 s7, s7, 0x8c00
	s_add_i32 s12, s7, 0
	v_add3_u32 v0, s12, v195, v166
	v_lshl_add_u32 v254, s6, 2, v196
	ds_read_b32 v254, v254
	ds_read_b128 v[2:5], v0
	ds_read_b128 v[6:9], v0 offset:32
	ds_read_b128 v[10:13], v0 offset:8704
	ds_read_b128 v[202:205], v0 offset:8736
	s_waitcnt lgkmcnt(3)
	v_mfma_f32_32x32x16_bf16 v[96:111], v[2:5], v[112:115], 0
	ds_read_b128 v[2:5], v0 offset:64
	ds_read_b128 v[206:209], v0 offset:8768
	s_waitcnt lgkmcnt(3)
	v_mfma_f32_32x32x16_bf16 v[64:79], v[10:13], v[112:115], 0
	v_mfma_f32_32x32x16_bf16 v[96:111], v[6:9], v[116:119], v[96:111]
	ds_read_b128 v[6:9], v0 offset:96
	ds_read_b128 v[10:13], v0 offset:8800
	s_waitcnt lgkmcnt(4)
	v_mfma_f32_32x32x16_bf16 v[64:79], v[202:205], v[116:119], v[64:79]
	s_waitcnt lgkmcnt(3)
	v_mfma_f32_32x32x16_bf16 v[96:111], v[2:5], v[120:123], v[96:111]
	ds_read_b128 v[2:5], v0 offset:128
	ds_read_b128 v[202:205], v0 offset:8832
	s_waitcnt lgkmcnt(4)
	v_mfma_f32_32x32x16_bf16 v[64:79], v[206:209], v[120:123], v[64:79]
	s_waitcnt lgkmcnt(3)
	v_mfma_f32_32x32x16_bf16 v[96:111], v[6:9], v[124:127], v[96:111]
	ds_read_b128 v[6:9], v0 offset:160
	ds_read_b128 v[206:209], v0 offset:8864
	s_waitcnt lgkmcnt(4)
	v_mfma_f32_32x32x16_bf16 v[64:79], v[10:13], v[124:127], v[64:79]
	s_waitcnt lgkmcnt(3)
	v_mfma_f32_32x32x16_bf16 v[96:111], v[2:5], v[128:131], v[96:111]
	ds_read_b128 v[2:5], v0 offset:192
	ds_read_b128 v[10:13], v0 offset:8896
	s_waitcnt lgkmcnt(4)
	v_mfma_f32_32x32x16_bf16 v[64:79], v[202:205], v[128:131], v[64:79]
	s_waitcnt lgkmcnt(3)
	v_mfma_f32_32x32x16_bf16 v[96:111], v[6:9], v[132:135], v[96:111]
	ds_read_b128 v[6:9], v0 offset:224
	ds_read_b128 v[202:205], v0 offset:8928
	s_waitcnt lgkmcnt(4)
	v_mfma_f32_32x32x16_bf16 v[64:79], v[206:209], v[132:135], v[64:79]
	s_waitcnt lgkmcnt(3)
	v_mfma_f32_32x32x16_bf16 v[96:111], v[2:5], v[136:139], v[96:111]
	s_waitcnt lgkmcnt(2)
	v_mfma_f32_32x32x16_bf16 v[64:79], v[10:13], v[136:139], v[64:79]
	s_waitcnt lgkmcnt(1)
	v_mfma_f32_32x32x16_bf16 v[96:111], v[6:9], v[140:143], v[96:111]
	s_waitcnt lgkmcnt(0)
	v_mfma_f32_32x32x16_bf16 v[64:79], v[202:205], v[140:143], v[64:79]
	v_and_b32_e32 v0, s8, v254
	v_cmp_eq_u32_e32 vcc, 0, v0
	s_cmp_eq_u32 s11, s97
	s_cbranch_scc1 .Lsel_lastmask
	s_nop 6
	v_cndmask_b32_e32 v2, v96, v185, vcc
	v_cndmask_b32_e32 v5, v64, v185, vcc
	v_cndmask_b32_e32 v3, v97, v185, vcc
	v_cndmask_b32_e32 v7, v65, v185, vcc
	v_cndmask_b32_e32 v4, v98, v185, vcc
	v_cndmask_b32_e32 v8, v66, v185, vcc
	v_cndmask_b32_e32 v9, v99, v185, vcc
	v_cndmask_b32_e32 v14, v67, v185, vcc
	v_cndmask_b32_e32 v6, v100, v185, vcc
	v_cndmask_b32_e32 v11, v68, v185, vcc
	v_cndmask_b32_e32 v12, v101, v185, vcc
	v_cndmask_b32_e32 v66, v69, v185, vcc
	v_cndmask_b32_e32 v10, v102, v185, vcc
	v_cndmask_b32_e32 v15, v70, v185, vcc
	v_cndmask_b32_e32 v64, v103, v185, vcc
	v_cndmask_b32_e32 v70, v71, v185, vcc
	v_cndmask_b32_e32 v13, v104, v185, vcc
	v_cndmask_b32_e32 v67, v72, v185, vcc
	v_cndmask_b32_e32 v68, v105, v185, vcc
	v_cndmask_b32_e32 v96, v73, v185, vcc
	v_cndmask_b32_e32 v65, v106, v185, vcc
	v_cndmask_b32_e32 v71, v74, v185, vcc
	v_cndmask_b32_e32 v72, v107, v185, vcc
	v_cndmask_b32_e32 v97, v75, v185, vcc
	v_cndmask_b32_e32 v69, v108, v185, vcc
	v_cndmask_b32_e32 v74, v76, v185, vcc
	v_cndmask_b32_e32 v75, v109, v185, vcc
	v_cndmask_b32_e32 v98, v77, v185, vcc
	v_cndmask_b32_e32 v73, v110, v185, vcc
	v_cndmask_b32_e32 v76, v78, v185, vcc
	v_cndmask_b32_e32 v77, v111, v185, vcc
	v_cndmask_b32_e32 v78, v79, v185, vcc
	s_branch .Lsel_join
.Lsel_lastmask:
	s_nop 3
	v_add_u32_e32 v201, s60, v197
	v_add_u32_e32 v3, 0xffffff80, v201
	v_cmp_gt_i32_e64 s[6:7], v3, v164
	s_or_b64 s[6:7], vcc, s[6:7]
	v_add_u32_e32 v0, 0xffffffa0, v201
	v_cndmask_b32_e64 v2, v96, v185, s[6:7]
	v_cmp_gt_i32_e64 s[6:7], v0, v164
	s_or_b64 s[6:7], vcc, s[6:7]
	v_add_u32_e32 v0, 0xffffffa1, v201
	v_cndmask_b32_e64 v5, v64, v185, s[6:7]
	v_cmp_ge_i32_e64 s[6:7], v3, v164
	s_or_b64 s[6:7], vcc, s[6:7]
	s_nop 0
	v_cndmask_b32_e64 v3, v97, v185, s[6:7]
	v_cmp_gt_i32_e64 s[6:7], v0, v164
	s_or_b64 s[6:7], vcc, s[6:7]
	v_add_u32_e32 v0, 0xffffff82, v201
	v_cndmask_b32_e64 v7, v65, v185, s[6:7]
	v_cmp_gt_i32_e64 s[6:7], v0, v164
	s_or_b64 s[6:7], vcc, s[6:7]
	v_add_u32_e32 v0, 0xffffffa2, v201
	v_cndmask_b32_e64 v4, v98, v185, s[6:7]
	v_cmp_gt_i32_e64 s[6:7], v0, v164
	s_or_b64 s[6:7], vcc, s[6:7]
	v_add_u32_e32 v0, 0xffffff83, v201
	v_cndmask_b32_e64 v8, v66, v185, s[6:7]
	v_cmp_gt_i32_e64 s[6:7], v0, v164
	s_or_b64 s[6:7], vcc, s[6:7]
	v_add_u32_e32 v0, 0xffffffa3, v201
	v_cndmask_b32_e64 v9, v99, v185, s[6:7]
	v_cmp_gt_i32_e64 s[6:7], v0, v164
	s_or_b64 s[6:7], vcc, s[6:7]
	v_add_u32_e32 v0, 0xffffff88, v201
	v_cndmask_b32_e64 v14, v67, v185, s[6:7]
	v_cmp_gt_i32_e64 s[6:7], v0, v164
	s_or_b64 s[6:7], vcc, s[6:7]
	v_add_u32_e32 v0, 0xffffffa8, v201
	v_cndmask_b32_e64 v6, v100, v185, s[6:7]
	v_cmp_gt_i32_e64 s[6:7], v0, v164
	s_or_b64 s[6:7], vcc, s[6:7]
	v_add_u32_e32 v0, 0xffffff89, v201
	v_cndmask_b32_e64 v11, v68, v185, s[6:7]
	v_cmp_gt_i32_e64 s[6:7], v0, v164
	s_or_b64 s[6:7], vcc, s[6:7]
	v_add_u32_e32 v0, 0xffffffa9, v201
	v_cndmask_b32_e64 v12, v101, v185, s[6:7]
	v_cmp_gt_i32_e64 s[6:7], v0, v164
	s_or_b64 s[6:7], vcc, s[6:7]
	v_add_u32_e32 v0, 0xffffff8a, v201
	v_cndmask_b32_e64 v66, v69, v185, s[6:7]
	v_cmp_gt_i32_e64 s[6:7], v0, v164
	s_or_b64 s[6:7], vcc, s[6:7]
; __device__ __forceinline__ int crow(int r, int hi) { return (r & 3) + 8 * (r >> 2) + 4 * hi; }
; template <bool WITH_O>
; __device__ __forceinline__ void softmax_step(float& m, float& l, f32x16 (&o)[4], f32x16& p0, f32x16& p1, LAS float* wsf, int r32, int hi) {
;     float mxa = fmaxf(fmaxf(p0[0], p1[0]), p0[1]), mxb = fmaxf(fmaxf(p1[1], p0[2]), p1[2]);
; #pragma unroll
;     for (int r = 3; r < 15; r += 2) { mxa = fmaxf(fmaxf(mxa, p0[r]), p1[r]); mxb = fmaxf(fmaxf(mxb, p0[r + 1]), p1[r + 1]); }
;     float mx = fmaxf(fmaxf(mxa, mxb), fmaxf(p0[15], p1[15]));
;     mx = fmaxf(mx, __shfl_xor(mx, 32));
;     const bool grow = __any(mx > m + 8.f);
;     const float mnew = grow ? fmaxf(m, mx) : m;
;     const float f = grow ? __builtin_amdgcn_exp2f(m - mnew) : 1.f;
;     m = mnew;
;     float s = 0.f;
; #pragma unroll
;     for (int r = 0; r < 16; ++r) { p0[r] = __builtin_amdgcn_exp2f(p0[r] - mnew); p1[r] = __builtin_amdgcn_exp2f(p1[r] - mnew); s += p0[r] + p1[r]; }
;     l = l * f + s;
;     if (WITH_O) {
;         if (grow) {
;             if (hi == 0) wsf[r32] = f;
;             asm volatile("s_waitcnt lgkmcnt(0)" ::: "memory");
; #pragma unroll
;             for (int r = 0; r < 16; ++r) { const float fr = wsf[crow(r, hi)];
; #pragma unroll
;                 for (int db = 0; db < 4; ++db) o[db][r] *= fr; }
; __device__ __forceinline__ void nsa_unit(int hk, int T, LAS unsigned char* lds, LAS float* wsf, const AttnPtrs& P) {
;     ...
;                 for (int r = 0; r < 16; ++r) { const int key = 64 * j + crow(r, hi);
;                     if (!mine || key > tq) p0[r] = -INFINITY; if (!mine || key + 32 > tq) p1[r] = -INFINITY; }
	v_add_u32_e32 v0, 0xffffffaa, v201
	v_cndmask_b32_e64 v10, v102, v185, s[6:7]
	v_cmp_gt_i32_e64 s[6:7], v0, v164
	s_or_b64 s[6:7], vcc, s[6:7]
	v_add_u32_e32 v0, 0xffffff8b, v201
	v_cndmask_b32_e64 v15, v70, v185, s[6:7]
	v_cmp_gt_i32_e64 s[6:7], v0, v164
	s_or_b64 s[6:7], vcc, s[6:7]
	v_add_u32_e32 v0, 0xffffffab, v201
	v_cndmask_b32_e64 v64, v103, v185, s[6:7]
	v_cmp_gt_i32_e64 s[6:7], v0, v164
	s_or_b64 s[6:7], vcc, s[6:7]
	v_add_u32_e32 v0, 0xffffff90, v201
	v_cndmask_b32_e64 v70, v71, v185, s[6:7]
	v_cmp_gt_i32_e64 s[6:7], v0, v164
	s_or_b64 s[6:7], vcc, s[6:7]
	v_add_u32_e32 v0, 0xffffffb0, v201
	v_cndmask_b32_e64 v13, v104, v185, s[6:7]
	v_cmp_gt_i32_e64 s[6:7], v0, v164
	s_or_b64 s[6:7], vcc, s[6:7]
	v_add_u32_e32 v0, 0xffffff91, v201
	v_cndmask_b32_e64 v67, v72, v185, s[6:7]
	v_cmp_gt_i32_e64 s[6:7], v0, v164
	s_or_b64 s[6:7], vcc, s[6:7]
	v_add_u32_e32 v0, 0xffffffb1, v201
	v_cndmask_b32_e64 v68, v105, v185, s[6:7]
	v_cmp_gt_i32_e64 s[6:7], v0, v164
	s_or_b64 s[6:7], vcc, s[6:7]
	v_add_u32_e32 v0, 0xffffff92, v201
	v_cndmask_b32_e64 v96, v73, v185, s[6:7]
	v_cmp_gt_i32_e64 s[6:7], v0, v164
	s_or_b64 s[6:7], vcc, s[6:7]
	v_add_u32_e32 v0, 0xffffffb2, v201
	v_cndmask_b32_e64 v65, v106, v185, s[6:7]
	v_cmp_gt_i32_e64 s[6:7], v0, v164
	s_or_b64 s[6:7], vcc, s[6:7]
	v_add_u32_e32 v0, 0xffffff93, v201
	v_cndmask_b32_e64 v71, v74, v185, s[6:7]
	v_cmp_gt_i32_e64 s[6:7], v0, v164
	s_or_b64 s[6:7], vcc, s[6:7]
	v_add_u32_e32 v0, 0xffffffb3, v201
	v_cndmask_b32_e64 v72, v107, v185, s[6:7]
	v_cmp_gt_i32_e64 s[6:7], v0, v164
	s_or_b64 s[6:7], vcc, s[6:7]
	v_add_u32_e32 v0, 0xffffff98, v201
	v_cndmask_b32_e64 v97, v75, v185, s[6:7]
	v_cmp_gt_i32_e64 s[6:7], v0, v164
	s_or_b64 s[6:7], vcc, s[6:7]
	v_add_u32_e32 v0, 0xffffffb8, v201
	v_cndmask_b32_e64 v69, v108, v185, s[6:7]
	v_cmp_gt_i32_e64 s[6:7], v0, v164
	s_or_b64 s[6:7], vcc, s[6:7]
	v_add_u32_e32 v0, 0xffffff99, v201
	v_cndmask_b32_e64 v74, v76, v185, s[6:7]
	v_cmp_gt_i32_e64 s[6:7], v0, v164
	s_or_b64 s[6:7], vcc, s[6:7]
	v_add_u32_e32 v0, 0xffffffb9, v201
	v_cndmask_b32_e64 v75, v109, v185, s[6:7]
	v_cmp_gt_i32_e64 s[6:7], v0, v164
	s_or_b64 s[6:7], vcc, s[6:7]
	v_add_u32_e32 v0, 0xffffff9a, v201
	v_cndmask_b32_e64 v98, v77, v185, s[6:7]
	v_cmp_gt_i32_e64 s[6:7], v0, v164
	s_or_b64 s[6:7], vcc, s[6:7]
	v_add_u32_e32 v0, 0xffffffba, v201
	v_cndmask_b32_e64 v73, v110, v185, s[6:7]
	v_cmp_gt_i32_e64 s[6:7], v0, v164
	s_or_b64 s[6:7], vcc, s[6:7]
	v_add_u32_e32 v0, 0xffffff9b, v201
	v_cndmask_b32_e64 v76, v78, v185, s[6:7]
	v_cmp_gt_i32_e64 s[6:7], v0, v164
	s_or_b64 s[6:7], vcc, s[6:7]
	v_add_u32_e32 v0, 0xffffffbb, v201
	v_cndmask_b32_e64 v77, v111, v185, s[6:7]
	v_cmp_gt_i32_e64 s[6:7], v0, v164
	s_or_b64 vcc, vcc, s[6:7]
	v_cndmask_b32_e32 v78, v79, v185, vcc
.Lsel_join:
	v_max3_f32 v0, v2, v5, v3
	v_max3_f32 v79, v7, v4, v8
	v_max3_f32 v0, v0, v9, v14
	v_max3_f32 v79, v79, v6, v11
	v_max3_f32 v0, v0, v12, v66
	v_max3_f32 v79, v79, v10, v15
	v_max3_f32 v0, v0, v64, v70
	v_max3_f32 v79, v79, v13, v67
	v_max3_f32 v0, v0, v68, v96
	v_max3_f32 v79, v79, v65, v71
	v_max3_f32 v0, v0, v72, v97
	v_max3_f32 v79, v79, v69, v74
	v_max_f32_e32 v99, v78, v78
	v_max_f32_e32 v100, v77, v77
	v_max3_f32 v0, v0, v75, v98
	v_max3_f32 v79, v79, v73, v76
	v_max_f32_e32 v99, v100, v99
	v_max3_f32 v0, v0, v79, v99
	ds_bpermute_b32 v79, v188, v0
	s_waitcnt lgkmcnt(0)
	v_max_f32_e32 v79, v79, v79
	v_max_f32_e32 v0, v0, v79
	v_add_f32_e32 v79, 0x41000000, v200
	v_cmp_gt_f32_e32 vcc, v0, v79
	s_cmp_eq_u64 vcc, 0
	v_max_f32_e32 v79, v200, v200
	v_max_f32_e32 v0, v79, v0
	s_cselect_b64 s[6:7], -1, 0
	v_cndmask_b32_e64 v0, v0, v200, s[6:7]
	v_sub_f32_e32 v79, v200, v0
	v_exp_f32_e32 v79, v79
	s_and_b64 vcc, exec, s[6:7]
	s_cbranch_vccnz .LBB0_1463
	s_and_saveexec_b64 s[8:9], s[4:5]
	ds_write_b32 v192, v79
	s_or_b64 exec, exec, s[8:9]
	s_waitcnt lgkmcnt(0)
	ds_read_b128 v[100:103], v193 offset:96
	ds_read_b128 v[104:107], v193 offset:64
	ds_read_b128 v[108:111], v193 offset:32
	ds_read_b128 v[200:203], v193
	s_waitcnt lgkmcnt(3)
	v_pk_mul_f32 v[60:61], v[60:61], v[100:101]
	s_waitcnt lgkmcnt(2)
	v_pk_mul_f32 v[56:57], v[56:57], v[104:105]
	s_waitcnt lgkmcnt(1)
	v_pk_mul_f32 v[52:53], v[52:53], v[108:109]
	v_pk_mul_f32 v[62:63], v[62:63], v[102:103]
	v_pk_mul_f32 v[58:59], v[58:59], v[106:107]
	v_pk_mul_f32 v[54:55], v[54:55], v[110:111]
	s_waitcnt lgkmcnt(0)
	v_pk_mul_f32 v[50:51], v[50:51], v[202:203]
	v_pk_mul_f32 v[48:49], v[48:49], v[200:201]
	v_pk_mul_f32 v[44:45], v[44:45], v[100:101]
	v_pk_mul_f32 v[40:41], v[40:41], v[104:105]
	v_pk_mul_f32 v[36:37], v[36:37], v[108:109]
	v_pk_mul_f32 v[46:47], v[46:47], v[102:103]
	v_pk_mul_f32 v[42:43], v[42:43], v[106:107]
	v_pk_mul_f32 v[38:39], v[38:39], v[110:111]
	v_pk_mul_f32 v[34:35], v[34:35], v[202:203]
	v_pk_mul_f32 v[32:33], v[32:33], v[200:201]
	v_pk_mul_f32 v[28:29], v[28:29], v[100:101]
	v_pk_mul_f32 v[24:25], v[24:25], v[104:105]
	v_pk_mul_f32 v[20:21], v[20:21], v[108:109]
	v_pk_mul_f32 v[30:31], v[30:31], v[102:103]
	v_pk_mul_f32 v[26:27], v[26:27], v[106:107]
	v_pk_mul_f32 v[22:23], v[22:23], v[110:111]
	v_pk_mul_f32 v[18:19], v[18:19], v[202:203]
	v_pk_mul_f32 v[16:17], v[16:17], v[200:201]
	v_pk_mul_f32 v[92:93], v[92:93], v[100:101]
	v_pk_mul_f32 v[88:89], v[88:89], v[104:105]
	v_pk_mul_f32 v[84:85], v[84:85], v[108:109]
	v_pk_mul_f32 v[94:95], v[94:95], v[102:103]
	v_pk_mul_f32 v[90:91], v[90:91], v[106:107]
	v_pk_mul_f32 v[86:87], v[86:87], v[110:111]
	v_pk_mul_f32 v[82:83], v[82:83], v[202:203]
	v_pk_mul_f32 v[80:81], v[80:81], v[200:201]

; __device__ __forceinline__ void nsa_unit(int hk, int T, LAS unsigned char* lds, LAS float* wsf, const AttnPtrs& P) {
;     ...
;             mid();
;             if (act) pv_tile(o, p0, p1, buf + 64 * KRS_NSA, r32, hi);
.LBB0_1464:
	s_waitcnt lgkmcnt(0)
	v_mov_b32_e32 v0, v200

; __global__ void __launch_bounds__(NTHREADS) mega_fwd(Args args) {
	.amdhsa_kernel _Z8mega_fwd4Args
		.amdhsa_group_segment_fixed_size 0
		.amdhsa_private_segment_fixed_size 0
		.amdhsa_kernarg_size 488
		.amdhsa_user_sgpr_count 2
		.amdhsa_user_sgpr_dispatch_ptr 0
		.amdhsa_user_sgpr_queue_ptr 0
		.amdhsa_user_sgpr_kernarg_segment_ptr 1
		.amdhsa_user_sgpr_dispatch_id 0
		.amdhsa_user_sgpr_kernarg_preload_length 0
		.amdhsa_user_sgpr_kernarg_preload_offset 0
		.amdhsa_user_sgpr_private_segment_size 0
		.amdhsa_uses_dynamic_stack 0
		.amdhsa_enable_private_segment 0
		.amdhsa_system_sgpr_workgroup_id_x 1
		.amdhsa_system_sgpr_workgroup_id_y 0
		.amdhsa_system_sgpr_workgroup_id_z 0
		.amdhsa_system_sgpr_workgroup_info 0
		.amdhsa_system_vgpr_workitem_id 2
		.amdhsa_next_free_vgpr 256
		.amdhsa_next_free_sgpr 98
		.amdhsa_accum_offset 256
		.amdhsa_reserve_vcc 1
		.amdhsa_float_round_mode_32 0
		.amdhsa_float_round_mode_16_64 0
		.amdhsa_float_denorm_mode_32 3
		.amdhsa_float_denorm_mode_16_64 3
		.amdhsa_dx10_clamp 1
		.amdhsa_ieee_mode 1
		.amdhsa_fp16_overflow 0
		.amdhsa_tg_split 0
		.amdhsa_exception_fp_ieee_invalid_op 0
		.amdhsa_exception_fp_denorm_src 0
		.amdhsa_exception_fp_ieee_div_zero 0
		.amdhsa_exception_fp_ieee_overflow 0
		.amdhsa_exception_fp_ieee_underflow 0
		.amdhsa_exception_fp_ieee_inexact 0
		.amdhsa_exception_int_div_zero 0
	.end_amdhsa_kernel

; __global__ void __launch_bounds__(NTHREADS) mega_fwd(Args args) {
.Lfunc_end0:
	.size	_Z8mega_fwd4Args, .Lfunc_end0-_Z8mega_fwd4Args
	.set _Z8mega_fwd4Args.num_vgpr, 256
	.set _Z8mega_fwd4Args.num_agpr, 0
	.set _Z8mega_fwd4Args.numbered_sgpr, 98
	.set _Z8mega_fwd4Args.num_named_barrier, 0
	.set _Z8mega_fwd4Args.private_seg_size, 0
	.set _Z8mega_fwd4Args.uses_vcc, 1
	.set _Z8mega_fwd4Args.uses_flat_scratch, 0
	.set _Z8mega_fwd4Args.has_dyn_sized_stack, 0
	.set _Z8mega_fwd4Args.has_recursion, 0
	.set _Z8mega_fwd4Args.has_indirect_call, 0

; __global__ void __launch_bounds__(NTHREADS) mega_fwd(Args args) {
amdhsa.kernels:
  - .agpr_count:     0
    .args:
      - .offset:         0
        .size:           232
        .value_kind:     by_value
      - .offset:         232
        .size:           4
        .value_kind:     hidden_block_count_x
      - .offset:         236
        .size:           4
        .value_kind:     hidden_block_count_y
      - .offset:         240
        .size:           4
        .value_kind:     hidden_block_count_z
      - .offset:         244
        .size:           2
        .value_kind:     hidden_group_size_x
      - .offset:         246
        .size:           2
        .value_kind:     hidden_group_size_y
      - .offset:         248
        .size:           2
        .value_kind:     hidden_group_size_z
      - .offset:         250
        .size:           2
        .value_kind:     hidden_remainder_x
      - .offset:         252
        .size:           2
        .value_kind:     hidden_remainder_y
      - .offset:         254
        .size:           2
        .value_kind:     hidden_remainder_z
      - .offset:         272
        .size:           8
        .value_kind:     hidden_global_offset_x
      - .offset:         280
        .size:           8
        .value_kind:     hidden_global_offset_y
      - .offset:         288
        .size:           8
        .value_kind:     hidden_global_offset_z
      - .offset:         296
        .size:           2
        .value_kind:     hidden_grid_dims
      - .offset:         320
        .size:           8
        .value_kind:     hidden_multigrid_sync_arg
      - .offset:         352
        .size:           4
        .value_kind:     hidden_dynamic_lds_size
    .group_segment_fixed_size: 0
    .kernarg_segment_align: 8
    .kernarg_segment_size: 488
    .language:       OpenCL C
    .language_version:
      - 2
      - 0
    .max_flat_workgroup_size: 512
    .name:           _Z8mega_fwd4Args
    .private_segment_fixed_size: 0
    .sgpr_count:     104
    .sgpr_spill_count: 37
    .symbol:         _Z8mega_fwd4Args.kd
    .uniform_work_group_size: 1
    .uses_dynamic_stack: false
    .vgpr_count:     256
    .vgpr_spill_count: 0
    .wavefront_size: 64
